# P1 row loop software-pipelined: next row's x loads issued per 4-piece chunk after that chunk is normalised and stored
# speedup vs baseline: 1.0226x; 1.0025x over previous
.LBB0_114:
	s_or_b64 exec, exec, s[8:9]
	v_readlane_b32 s0, v255, 5
	s_cmp_ge_i32 s0, s3
	s_waitcnt lgkmcnt(0)
	s_barrier
	s_cbranch_scc1 .LBB0_117
	v_mov_b32_e32 v1, 0
	v_lshlrev_b32_e32 v2, 3, v222
	v_mov_b32_e32 v3, v1
	v_lshl_add_u64 v[26:27], s[14:15], 0, v[2:3]
	v_lshlrev_b32_e32 v2, 2, v222
	v_lshlrev_b32_e32 v0, 4, v222
	v_lshl_add_u64 v[2:3], s[70:71], 0, v[2:3]
	s_mov_b64 s[0:1], 0x1f800000
	v_lshl_add_u64 v[24:25], s[36:37], 0, v[0:1]
	v_lshl_add_u64 v[28:29], v[2:3], 0, s[0:1]
	v_add_u32_e32 v36, 0, v0
	s_movk_i32 s6, 0x1000
	s_movk_i32 s7, 0x2000
	s_movk_i32 s8, 0x3000
	v_mov_b32_e32 v37, 0x358637bd
	s_mov_b32 s9, 0xf800000
	v_mov_b32_e32 v38, 0x260
	s_mov_b32 s10, 0xc3e00000
	v_mov_b32_e32 v39, 0x43e00000
	v_readlane_b32 s11, v255, 5
	s_mov_b64 s[26:27], 0x1000
	s_mov_b64 s[30:31], 0x2000
	s_mov_b64 s[34:35], 0x3000
	s_add_i32 s23, s16, s11
	v_mov_b32_e32 v162, s23
	v_mov_b32_e32 v163, 0
	v_lshlrev_b64 v[162:163], 14, v[162:163]
	v_lshl_add_u64 v[160:161], v[162:163], 0, v[24:25]
	v_lshl_add_u64 v[164:165], v[160:161], 0, s[26:27]
	v_lshl_add_u64 v[166:167], v[160:161], 0, s[30:31]
	v_lshl_add_u64 v[168:169], v[160:161], 0, s[34:35]
	global_load_dwordx4 v[64:67], v[160:161], off nt
	global_load_dwordx4 v[68:71], v[160:161], off offset:1024 nt
	global_load_dwordx4 v[72:75], v[160:161], off offset:2048 nt
	global_load_dwordx4 v[76:79], v[160:161], off offset:3072 nt
	global_load_dwordx4 v[80:83], v[164:165], off nt
	global_load_dwordx4 v[84:87], v[164:165], off offset:1024 nt
	global_load_dwordx4 v[88:91], v[164:165], off offset:2048 nt
	global_load_dwordx4 v[92:95], v[164:165], off offset:3072 nt
	global_load_dwordx4 v[96:99], v[166:167], off nt
	global_load_dwordx4 v[100:103], v[166:167], off offset:1024 nt
	global_load_dwordx4 v[104:107], v[166:167], off offset:2048 nt
	global_load_dwordx4 v[108:111], v[166:167], off offset:3072 nt
	global_load_dwordx4 v[112:115], v[168:169], off nt
	global_load_dwordx4 v[116:119], v[168:169], off offset:1024 nt
	global_load_dwordx4 v[120:123], v[168:169], off offset:2048 nt
	global_load_dwordx4 v[124:127], v[168:169], off offset:3072 nt
.LBB0_116:
	s_add_i32 s0, s16, s11
	s_ashr_i32 s1, s0, 31
	s_lshl_b64 s[18:19], s[0:1], 14
	ds_read_b128 v[4:7], v36
	ds_read_b128 v[0:3], v36 offset:1024
	ds_read_b128 v[12:15], v36 offset:16384
	ds_read_b128 v[8:11], v36 offset:17408
	ds_read_b128 v[16:19], v36 offset:2048
	ds_read_b128 v[20:23], v36 offset:3072
	ds_read_b128 v[56:59], v36 offset:18432
	ds_read_b128 v[60:63], v36 offset:19456
	s_lshl_b64 s[20:21], s[0:1], 12
	s_nop 0
	s_lshl_b64 s[0:1], s[0:1], 13
	s_nop 0
	v_lshl_add_u64 v[34:35], v[26:27], 0, s[0:1]
	s_nop 0
	s_nop 0
	s_nop 0
	s_nop 0
	s_nop 0
	s_nop 0
	v_add_co_u32_e32 v32, vcc, s6, v34
	v_mov_b32_e32 v40, 0
	s_nop 0
	v_addc_co_u32_e32 v33, vcc, 0, v35, vcc
	v_mov_b32_e32 v41, 0
	v_mov_b32_e32 v43, 0
	v_mov_b32_e32 v45, 0
	v_lshl_add_u64 v[30:31], v[28:29], 0, s[20:21]
	v_mov_b32_e32 v42, 0
	v_mov_b32_e32 v44, 0
	v_mov_b32_e32 v47, 0
	v_mov_b32_e32 v49, 0
	v_mov_b32_e32 v46, 0
	v_mov_b32_e32 v48, 0
	v_mov_b32_e32 v51, 0
	v_mov_b32_e32 v53, 0
	v_mov_b32_e32 v50, 0
	v_mov_b32_e32 v52, 0
	v_mov_b32_e32 v54, 0
	v_mov_b32_e32 v55, 0
	s_add_i32 s11, s11, 8
	s_add_i32 s23, s16, s11
	s_cmp_lt_i32 s11, s3
	v_mov_b32_e32 v162, s23
	v_mov_b32_e32 v163, 0
	v_lshlrev_b64 v[162:163], 14, v[162:163]
	v_lshl_add_u64 v[160:161], v[162:163], 0, v[24:25]
	v_lshl_add_u64 v[164:165], v[160:161], 0, s[26:27]
	v_lshl_add_u64 v[166:167], v[160:161], 0, s[30:31]
	v_lshl_add_u64 v[168:169], v[160:161], 0, s[34:35]
	s_waitcnt vmcnt(15)
	v_mul_f32_e32 v128, v65, v65
	v_mul_f32_e32 v129, v67, v67
	s_waitcnt vmcnt(14)
	v_mul_f32_e32 v130, v69, v69
	v_mul_f32_e32 v131, v71, v71
	s_waitcnt vmcnt(13)
	v_mul_f32_e32 v132, v73, v73
	v_mul_f32_e32 v133, v75, v75
	v_fmac_f32_e32 v128, v64, v64
	v_fmac_f32_e32 v129, v66, v66
	v_fmac_f32_e32 v130, v68, v68
	v_fmac_f32_e32 v131, v70, v70
	s_waitcnt vmcnt(12)
	v_mul_f32_e32 v134, v77, v77
	v_mul_f32_e32 v135, v79, v79
	v_fmac_f32_e32 v132, v72, v72
	v_fmac_f32_e32 v133, v74, v74
	v_add_f32_e32 v128, v128, v129
	v_add_f32_e32 v129, v130, v131
	v_fmac_f32_e32 v134, v76, v76
	v_fmac_f32_e32 v135, v78, v78
	s_waitcnt vmcnt(11)
	v_mul_f32_e32 v136, v81, v81
	v_mul_f32_e32 v137, v83, v83
	v_add_f32_e32 v130, v132, v133
	v_add_f32_e32 v128, v128, v129
	s_waitcnt vmcnt(10)
	v_mul_f32_e32 v138, v85, v85
	v_mul_f32_e32 v139, v87, v87
	v_add_f32_e32 v131, v134, v135
	v_fmac_f32_e32 v136, v80, v80
	v_fmac_f32_e32 v137, v82, v82
	v_add_f32_e32 v128, v128, v130
	s_waitcnt vmcnt(9)
	v_mul_f32_e32 v140, v89, v89
	v_mul_f32_e32 v141, v91, v91
	v_fmac_f32_e32 v138, v84, v84
	v_fmac_f32_e32 v139, v86, v86
	v_add_f32_e32 v129, v136, v137
	v_add_f32_e32 v128, v128, v131
	s_waitcnt vmcnt(8)
	v_mul_f32_e32 v142, v93, v93
	v_mul_f32_e32 v143, v95, v95
	v_fmac_f32_e32 v140, v88, v88
	v_fmac_f32_e32 v141, v90, v90
	v_add_f32_e32 v132, v138, v139
	v_add_f32_e32 v128, v128, v129
	s_waitcnt vmcnt(7)
	v_mul_f32_e32 v144, v97, v97
	v_mul_f32_e32 v145, v99, v99
	v_fmac_f32_e32 v142, v92, v92
	v_fmac_f32_e32 v143, v94, v94
	v_add_f32_e32 v133, v140, v141
	v_add_f32_e32 v128, v128, v132
	s_waitcnt vmcnt(6)
	v_mul_f32_e32 v146, v101, v101
	v_mul_f32_e32 v147, v103, v103
	v_fmac_f32_e32 v144, v96, v96
	v_fmac_f32_e32 v145, v98, v98
	v_add_f32_e32 v134, v142, v143
	v_add_f32_e32 v128, v128, v133
	s_waitcnt vmcnt(5)
	v_mul_f32_e32 v148, v105, v105
	v_mul_f32_e32 v149, v107, v107
	v_fmac_f32_e32 v146, v100, v100
	v_fmac_f32_e32 v147, v102, v102
	v_add_f32_e32 v135, v144, v145
	v_add_f32_e32 v128, v128, v134
	s_waitcnt vmcnt(4)
	v_mul_f32_e32 v150, v109, v109
	v_mul_f32_e32 v151, v111, v111
	v_fmac_f32_e32 v148, v104, v104
	v_fmac_f32_e32 v149, v106, v106
	v_add_f32_e32 v136, v146, v147
	v_add_f32_e32 v128, v128, v135
	s_waitcnt vmcnt(3)
	v_mul_f32_e32 v152, v113, v113
	v_mul_f32_e32 v153, v115, v115
	v_fmac_f32_e32 v150, v108, v108
	v_fmac_f32_e32 v151, v110, v110
	v_add_f32_e32 v137, v148, v149
	v_add_f32_e32 v128, v128, v136
	s_waitcnt vmcnt(2)
	v_mul_f32_e32 v154, v117, v117
	v_mul_f32_e32 v155, v119, v119
	v_fmac_f32_e32 v152, v112, v112
	v_fmac_f32_e32 v153, v114, v114
	v_add_f32_e32 v138, v150, v151
	v_add_f32_e32 v128, v128, v137
	s_waitcnt vmcnt(1)
	v_mul_f32_e32 v156, v121, v121
	v_mul_f32_e32 v157, v123, v123
	v_fmac_f32_e32 v154, v116, v116
	v_fmac_f32_e32 v155, v118, v118
	v_add_f32_e32 v139, v152, v153
	v_add_f32_e32 v128, v128, v138
	s_waitcnt vmcnt(0)
	v_mul_f32_e32 v158, v125, v125
	v_mul_f32_e32 v159, v127, v127
	v_fmac_f32_e32 v156, v120, v120
	v_fmac_f32_e32 v157, v122, v122
	v_add_f32_e32 v140, v154, v155
	v_add_f32_e32 v128, v128, v139
	v_fmac_f32_e32 v158, v124, v124
	v_fmac_f32_e32 v159, v126, v126
	v_add_f32_e32 v141, v156, v157
	v_add_f32_e32 v128, v128, v140
	v_add_f32_e32 v142, v158, v159
	v_add_f32_e32 v128, v128, v141
	v_add_f32_e32 v128, v128, v142
	s_nop 1
	v_add_f32_dpp v128, v128, v128 quad_perm:[1,0,3,2] row_mask:0xf bank_mask:0xf bound_ctrl:1
	s_nop 1
	v_add_f32_dpp v128, v128, v128 quad_perm:[2,3,0,1] row_mask:0xf bank_mask:0xf bound_ctrl:1
	s_nop 1
	v_add_f32_dpp v128, v128, v128 row_half_mirror row_mask:0xf bank_mask:0xf bound_ctrl:1
	s_nop 1
	v_add_f32_dpp v128, v128, v128 row_mirror row_mask:0xf bank_mask:0xf bound_ctrl:1
	v_mov_b32_e32 v129, v128
	s_nop 1
	v_permlane16_swap_b32_e32 v128, v129
	v_add_f32_e32 v128, v128, v129
	v_mov_b32_e32 v129, v128
	s_nop 1
	v_permlane32_swap_b32_e32 v128, v129
	v_add_f32_e32 v128, v128, v129
	v_fmamk_f32 v128, v128, 0x39800000, v37
	v_mul_f32_e32 v129, 0x4f800000, v128
	v_cmp_gt_f32_e32 vcc, s9, v128
	s_nop 1
	v_cndmask_b32_e32 v128, v128, v129, vcc
	v_sqrt_f32_e32 v129, v128
	s_nop 0
	v_add_u32_e32 v130, -1, v129
	v_add_u32_e32 v131, 1, v129
	v_fma_f32 v132, -v130, v129, v128
	v_fma_f32 v133, -v131, v129, v128
	v_cmp_ge_f32_e64 s[0:1], 0, v132
	s_nop 1
	v_cndmask_b32_e64 v129, v129, v130, s[0:1]
	v_cmp_lt_f32_e64 s[0:1], 0, v133
	s_nop 1
	v_cndmask_b32_e64 v129, v129, v131, s[0:1]
	v_mul_f32_e32 v130, 0x37800000, v129
	v_cndmask_b32_e32 v129, v129, v130, vcc
	v_cmp_class_f32_e32 vcc, v128, v38
	s_nop 1
	v_cndmask_b32_e32 v128, v129, v128, vcc
	v_div_scale_f32 v129, s[0:1], v128, v128, 1.0
	v_rcp_f32_e32 v131, v129
	v_div_scale_f32 v130, vcc, 1.0, v128, 1.0
	v_fma_f32 v132, -v129, v131, 1.0
	v_fmac_f32_e32 v131, v132, v131
	v_mul_f32_e32 v132, v130, v131
	v_fma_f32 v133, -v129, v132, v130
	v_fmac_f32_e32 v132, v133, v131
	v_fma_f32 v129, -v129, v132, v130
	v_div_fmas_f32 v129, v129, v131, v132
	v_div_fixup_f32 v128, v129, v128, 1.0
	v_pk_mul_f32 v[64:65], v[128:129], v[64:65] op_sel_hi:[0,1]
	v_pk_mul_f32 v[66:67], v[128:129], v[66:67] op_sel_hi:[0,1]
	v_pk_mul_f32 v[68:69], v[128:129], v[68:69] op_sel_hi:[0,1]
	v_pk_mul_f32 v[70:71], v[128:129], v[70:71] op_sel_hi:[0,1]
	v_pk_mul_f32 v[72:73], v[128:129], v[72:73] op_sel_hi:[0,1]
	v_pk_mul_f32 v[74:75], v[128:129], v[74:75] op_sel_hi:[0,1]
	s_waitcnt lgkmcnt(5)
	v_pk_fma_f32 v[6:7], v[14:15], v[66:67], v[6:7]
	v_pk_fma_f32 v[4:5], v[12:13], v[64:65], v[4:5]
	s_waitcnt lgkmcnt(4)
	v_pk_fma_f32 v[2:3], v[10:11], v[70:71], v[2:3]
	v_pk_fma_f32 v[0:1], v[8:9], v[68:69], v[0:1]
	s_waitcnt lgkmcnt(1)
	v_pk_fma_f32 v[8:9], v[58:59], v[74:75], v[18:19]
	v_pk_fma_f32 v[10:11], v[56:57], v[72:73], v[16:17]
	v_cvt_pk_f16_f32 v16, v4, v5
	v_cvt_pk_f16_f32 v17, v6, v7
	v_mul_f32_e32 v18, 0x41800000, v4
	v_mul_f32_e32 v19, 0x41800000, v5
	v_pk_mul_f32 v[76:77], v[128:129], v[76:77] op_sel_hi:[0,1]
	global_store_dwordx2 v[34:35], v[16:17], off
	v_med3_f32 v16, v18, s10, v39
	v_med3_f32 v17, v19, s10, v39
	s_waitcnt lgkmcnt(0)
	v_pk_fma_f32 v[14:15], v[60:61], v[76:77], v[20:21]
	v_mul_f32_e32 v20, 0x41800000, v0
	v_mul_f32_e32 v21, 0x41800000, v1
	v_cvt_pk_fp8_f32 v40, v16, v17
	v_pk_mul_f32 v[78:79], v[128:129], v[78:79] op_sel_hi:[0,1]
	v_med3_f32 v18, v20, s10, v39
	v_med3_f32 v19, v21, s10, v39
	v_pk_fma_f32 v[12:13], v[62:63], v[78:79], v[22:23]
	v_mul_f32_e32 v6, 0x41800000, v6
	v_mul_f32_e32 v7, 0x41800000, v7
	v_cvt_pk_f16_f32 v4, v0, v1
	v_cvt_pk_f16_f32 v5, v2, v3
	v_mul_f32_e32 v22, 0x41800000, v2
	v_cvt_pk_f16_f32 v0, v10, v11
	v_mul_f32_e32 v10, 0x41800000, v10
	v_mul_f32_e32 v11, 0x41800000, v11
	v_cvt_pk_f16_f32 v2, v14, v15
	v_mul_f32_e32 v14, 0x41800000, v14
	v_mul_f32_e32 v15, 0x41800000, v15
	v_cvt_pk_fp8_f32 v41, v18, v19
	v_med3_f32 v6, v6, s10, v39
	v_med3_f32 v7, v7, s10, v39
	v_med3_f32 v10, v10, s10, v39
	v_med3_f32 v11, v11, s10, v39
	v_med3_f32 v14, v14, s10, v39
	v_med3_f32 v15, v15, s10, v39
	v_mul_f32_e32 v23, 0x41800000, v3
	v_cvt_pk_fp8_f32 v43, v10, v11
	v_cvt_pk_fp8_f32 v45, v14, v15
	v_cvt_pk_fp8_f32 v40, v6, v7 op_sel:[0,0,1]
	v_med3_f32 v20, v22, s10, v39
	v_med3_f32 v21, v23, s10, v39
	v_cvt_pk_f16_f32 v1, v8, v9
	v_mul_f32_e32 v8, 0x41800000, v8
	v_mul_f32_e32 v9, 0x41800000, v9
	v_cvt_pk_f16_f32 v3, v12, v13
	v_mul_f32_e32 v12, 0x41800000, v12
	v_mul_f32_e32 v13, 0x41800000, v13
	v_cvt_pk_fp8_f32 v41, v20, v21 op_sel:[0,0,1]
	v_med3_f32 v8, v8, s10, v39
	v_med3_f32 v9, v9, s10, v39
	v_med3_f32 v12, v12, s10, v39
	v_med3_f32 v13, v13, s10, v39
	v_cvt_pk_fp8_f32 v43, v8, v9 op_sel:[0,0,1]
	v_cvt_pk_fp8_f32 v45, v12, v13 op_sel:[0,0,1]
	global_store_dword v[30:31], v40, off
	global_store_dwordx2 v[34:35], v[4:5], off offset:512
	global_store_dword v[30:31], v41, off offset:256
	global_store_dwordx2 v[34:35], v[0:1], off offset:1024
	global_store_dword v[30:31], v43, off offset:512
	global_store_dwordx2 v[34:35], v[2:3], off offset:1536
	global_store_dword v[30:31], v45, off offset:768
	s_cbranch_scc0 .Lp1_nopf0
	global_load_dwordx4 v[64:67], v[160:161], off nt
	global_load_dwordx4 v[68:71], v[160:161], off offset:1024 nt
	global_load_dwordx4 v[72:75], v[160:161], off offset:2048 nt
	global_load_dwordx4 v[76:79], v[160:161], off offset:3072 nt
.Lp1_nopf0:
	ds_read_b128 v[0:3], v36 offset:4096
	ds_read_b128 v[4:7], v36 offset:5120
	ds_read_b128 v[8:11], v36 offset:20480
	ds_read_b128 v[12:15], v36 offset:21504
	ds_read_b128 v[16:19], v36 offset:6144
	ds_read_b128 v[20:23], v36 offset:7168
	ds_read_b128 v[56:59], v36 offset:22528
	ds_read_b128 v[60:63], v36 offset:23552
	v_pk_mul_f32 v[80:81], v[128:129], v[80:81] op_sel_hi:[0,1]
	v_pk_mul_f32 v[82:83], v[128:129], v[82:83] op_sel_hi:[0,1]
	v_pk_mul_f32 v[88:89], v[128:129], v[88:89] op_sel_hi:[0,1]
	v_pk_mul_f32 v[90:91], v[128:129], v[90:91] op_sel_hi:[0,1]
	s_waitcnt lgkmcnt(5)
	v_pk_fma_f32 v[2:3], v[10:11], v[82:83], v[2:3]
	v_pk_fma_f32 v[0:1], v[8:9], v[80:81], v[0:1]
	v_pk_mul_f32 v[84:85], v[128:129], v[84:85] op_sel_hi:[0,1]
	s_waitcnt lgkmcnt(1)
	v_pk_fma_f32 v[8:9], v[58:59], v[90:91], v[18:19]
	v_pk_fma_f32 v[10:11], v[56:57], v[88:89], v[16:17]
	v_cvt_pk_f16_f32 v16, v0, v1
	v_cvt_pk_f16_f32 v17, v2, v3
	v_mul_f32_e32 v18, 0x41800000, v0
	v_mul_f32_e32 v19, 0x41800000, v1
	v_pk_mul_f32 v[86:87], v[128:129], v[86:87] op_sel_hi:[0,1]
	v_pk_mul_f32 v[92:93], v[128:129], v[92:93] op_sel_hi:[0,1]
	v_pk_mul_f32 v[94:95], v[128:129], v[94:95] op_sel_hi:[0,1]
	v_pk_fma_f32 v[4:5], v[12:13], v[84:85], v[4:5]
	global_store_dwordx2 v[34:35], v[16:17], off offset:2048
	v_med3_f32 v16, v18, s10, v39
	v_med3_f32 v17, v19, s10, v39
	v_pk_fma_f32 v[6:7], v[14:15], v[86:87], v[6:7]
	s_waitcnt lgkmcnt(0)
	v_pk_fma_f32 v[12:13], v[62:63], v[94:95], v[22:23]
	v_pk_fma_f32 v[14:15], v[60:61], v[92:93], v[20:21]
	v_mul_f32_e32 v20, 0x41800000, v2
	v_mul_f32_e32 v21, 0x41800000, v3
	v_mul_f32_e32 v22, 0x41800000, v4
	v_mul_f32_e32 v23, 0x41800000, v5
	v_cvt_pk_fp8_f32 v42, v16, v17
	v_med3_f32 v18, v20, s10, v39
	v_med3_f32 v19, v21, s10, v39
	v_med3_f32 v20, v22, s10, v39
	v_med3_f32 v21, v23, s10, v39
	v_cvt_pk_f16_f32 v0, v4, v5
	v_cvt_pk_f16_f32 v2, v10, v11
	v_mul_f32_e32 v10, 0x41800000, v10
	v_mul_f32_e32 v11, 0x41800000, v11
	v_cvt_pk_f16_f32 v4, v14, v15
	v_mul_f32_e32 v14, 0x41800000, v14
	v_mul_f32_e32 v15, 0x41800000, v15
	v_cvt_pk_fp8_f32 v44, v20, v21
	v_med3_f32 v10, v10, s10, v39
	v_med3_f32 v11, v11, s10, v39
	v_med3_f32 v14, v14, s10, v39
	v_med3_f32 v15, v15, s10, v39
	v_cvt_pk_f16_f32 v1, v6, v7
	v_mul_f32_e32 v6, 0x41800000, v6
	v_mul_f32_e32 v7, 0x41800000, v7
	v_cvt_pk_fp8_f32 v47, v10, v11
	v_cvt_pk_fp8_f32 v49, v14, v15
	v_cvt_pk_fp8_f32 v42, v18, v19 op_sel:[0,0,1]
	v_med3_f32 v6, v6, s10, v39
	v_med3_f32 v7, v7, s10, v39
	v_cvt_pk_f16_f32 v3, v8, v9
	v_mul_f32_e32 v8, 0x41800000, v8
	v_mul_f32_e32 v9, 0x41800000, v9
	v_cvt_pk_f16_f32 v5, v12, v13
	v_mul_f32_e32 v12, 0x41800000, v12
	v_mul_f32_e32 v13, 0x41800000, v13
	v_cvt_pk_fp8_f32 v44, v6, v7 op_sel:[0,0,1]
	v_med3_f32 v8, v8, s10, v39
	v_med3_f32 v9, v9, s10, v39
	v_med3_f32 v12, v12, s10, v39
	v_med3_f32 v13, v13, s10, v39
	v_cvt_pk_fp8_f32 v47, v8, v9 op_sel:[0,0,1]
	v_cvt_pk_fp8_f32 v49, v12, v13 op_sel:[0,0,1]
	global_store_dword v[30:31], v42, off offset:1024
	global_store_dwordx2 v[34:35], v[0:1], off offset:2560
	global_store_dword v[30:31], v44, off offset:1280
	global_store_dwordx2 v[34:35], v[2:3], off offset:3072
	global_store_dword v[30:31], v47, off offset:1536
	global_store_dwordx2 v[34:35], v[4:5], off offset:3584
	global_store_dword v[30:31], v49, off offset:1792
	s_cbranch_scc0 .Lp1_nopf1
	global_load_dwordx4 v[80:83], v[164:165], off nt
	global_load_dwordx4 v[84:87], v[164:165], off offset:1024 nt
	global_load_dwordx4 v[88:91], v[164:165], off offset:2048 nt
	global_load_dwordx4 v[92:95], v[164:165], off offset:3072 nt
.Lp1_nopf1:
	ds_read_b128 v[0:3], v36 offset:8192
	ds_read_b128 v[4:7], v36 offset:9216
	ds_read_b128 v[8:11], v36 offset:24576
	ds_read_b128 v[12:15], v36 offset:25600
	ds_read_b128 v[16:19], v36 offset:10240
	ds_read_b128 v[20:23], v36 offset:11264
	ds_read_b128 v[40:43], v36 offset:26624
	ds_read_b128 v[56:59], v36 offset:27648
	v_pk_mul_f32 v[96:97], v[128:129], v[96:97] op_sel_hi:[0,1]
	v_pk_mul_f32 v[98:99], v[128:129], v[98:99] op_sel_hi:[0,1]
	v_pk_mul_f32 v[104:105], v[128:129], v[104:105] op_sel_hi:[0,1]
	v_pk_mul_f32 v[106:107], v[128:129], v[106:107] op_sel_hi:[0,1]
	s_waitcnt lgkmcnt(5)
	v_pk_fma_f32 v[2:3], v[10:11], v[98:99], v[2:3]
	v_pk_fma_f32 v[0:1], v[8:9], v[96:97], v[0:1]
	v_pk_mul_f32 v[100:101], v[128:129], v[100:101] op_sel_hi:[0,1]
	s_waitcnt lgkmcnt(1)
	v_pk_fma_f32 v[8:9], v[42:43], v[106:107], v[18:19]
	v_pk_fma_f32 v[10:11], v[40:41], v[104:105], v[16:17]
	v_cvt_pk_f16_f32 v16, v0, v1
	v_cvt_pk_f16_f32 v17, v2, v3
	v_mul_f32_e32 v18, 0x41800000, v0
	v_mul_f32_e32 v19, 0x41800000, v1
	v_pk_mul_f32 v[102:103], v[128:129], v[102:103] op_sel_hi:[0,1]
	v_pk_mul_f32 v[108:109], v[128:129], v[108:109] op_sel_hi:[0,1]
	v_pk_mul_f32 v[110:111], v[128:129], v[110:111] op_sel_hi:[0,1]
	v_pk_fma_f32 v[4:5], v[12:13], v[100:101], v[4:5]
	global_store_dwordx2 v[32:33], v[16:17], off
	v_med3_f32 v16, v18, s10, v39
	v_med3_f32 v17, v19, s10, v39
	v_pk_fma_f32 v[6:7], v[14:15], v[102:103], v[6:7]
	s_waitcnt lgkmcnt(0)
	v_pk_fma_f32 v[12:13], v[58:59], v[110:111], v[22:23]
	v_pk_fma_f32 v[14:15], v[56:57], v[108:109], v[20:21]
	v_mul_f32_e32 v20, 0x41800000, v2
	v_mul_f32_e32 v21, 0x41800000, v3
	v_mul_f32_e32 v22, 0x41800000, v4
	v_mul_f32_e32 v23, 0x41800000, v5
	v_cvt_pk_fp8_f32 v46, v16, v17
	v_med3_f32 v18, v20, s10, v39
	v_med3_f32 v19, v21, s10, v39
	v_med3_f32 v20, v22, s10, v39
	v_med3_f32 v21, v23, s10, v39
	v_cvt_pk_f16_f32 v0, v4, v5
	v_cvt_pk_f16_f32 v2, v10, v11
	v_mul_f32_e32 v10, 0x41800000, v10
	v_mul_f32_e32 v11, 0x41800000, v11
	v_cvt_pk_f16_f32 v4, v14, v15
	v_mul_f32_e32 v14, 0x41800000, v14
	v_mul_f32_e32 v15, 0x41800000, v15
	v_cvt_pk_fp8_f32 v48, v20, v21
	v_med3_f32 v10, v10, s10, v39
	v_med3_f32 v11, v11, s10, v39
	v_med3_f32 v14, v14, s10, v39
	v_med3_f32 v15, v15, s10, v39
	v_cvt_pk_f16_f32 v1, v6, v7
	v_mul_f32_e32 v6, 0x41800000, v6
	v_mul_f32_e32 v7, 0x41800000, v7
	v_cvt_pk_fp8_f32 v51, v10, v11
	v_cvt_pk_fp8_f32 v53, v14, v15
	v_cvt_pk_fp8_f32 v46, v18, v19 op_sel:[0,0,1]
	v_med3_f32 v6, v6, s10, v39
	v_med3_f32 v7, v7, s10, v39
	v_cvt_pk_f16_f32 v3, v8, v9
	v_mul_f32_e32 v8, 0x41800000, v8
	v_mul_f32_e32 v9, 0x41800000, v9
	v_cvt_pk_f16_f32 v5, v12, v13
	v_mul_f32_e32 v12, 0x41800000, v12
	v_mul_f32_e32 v13, 0x41800000, v13
	v_cvt_pk_fp8_f32 v48, v6, v7 op_sel:[0,0,1]
	v_med3_f32 v8, v8, s10, v39
	v_med3_f32 v9, v9, s10, v39
	v_med3_f32 v12, v12, s10, v39
	v_med3_f32 v13, v13, s10, v39
	v_cvt_pk_fp8_f32 v51, v8, v9 op_sel:[0,0,1]
	v_cvt_pk_fp8_f32 v53, v12, v13 op_sel:[0,0,1]
	global_store_dword v[30:31], v46, off offset:2048
	global_store_dwordx2 v[32:33], v[0:1], off offset:512
	global_store_dword v[30:31], v48, off offset:2304
	global_store_dwordx2 v[32:33], v[2:3], off offset:1024
	global_store_dword v[30:31], v51, off offset:2560
	global_store_dwordx2 v[32:33], v[4:5], off offset:1536
	global_store_dword v[30:31], v53, off offset:2816
	s_cbranch_scc0 .Lp1_nopf2
	global_load_dwordx4 v[96:99], v[166:167], off nt
	global_load_dwordx4 v[100:103], v[166:167], off offset:1024 nt
	global_load_dwordx4 v[104:107], v[166:167], off offset:2048 nt
	global_load_dwordx4 v[108:111], v[166:167], off offset:3072 nt
.Lp1_nopf2:
	ds_read_b128 v[0:3], v36 offset:12288
	ds_read_b128 v[4:7], v36 offset:13312
	ds_read_b128 v[8:11], v36 offset:28672
	ds_read_b128 v[12:15], v36 offset:29696
	ds_read_b128 v[16:19], v36 offset:14336
	ds_read_b128 v[20:23], v36 offset:15360
	ds_read_b128 v[40:43], v36 offset:30720
	ds_read_b128 v[44:47], v36 offset:31744
	v_pk_mul_f32 v[112:113], v[128:129], v[112:113] op_sel_hi:[0,1]
	v_pk_mul_f32 v[114:115], v[128:129], v[114:115] op_sel_hi:[0,1]
	v_pk_mul_f32 v[120:121], v[128:129], v[120:121] op_sel_hi:[0,1]
	v_pk_mul_f32 v[122:123], v[128:129], v[122:123] op_sel_hi:[0,1]
	s_waitcnt lgkmcnt(5)
	v_pk_fma_f32 v[2:3], v[10:11], v[114:115], v[2:3]
	v_pk_fma_f32 v[0:1], v[8:9], v[112:113], v[0:1]
	v_pk_mul_f32 v[116:117], v[128:129], v[116:117] op_sel_hi:[0,1]
	s_waitcnt lgkmcnt(1)
	v_pk_fma_f32 v[8:9], v[42:43], v[122:123], v[18:19]
	v_pk_fma_f32 v[10:11], v[40:41], v[120:121], v[16:17]
	v_cvt_pk_f16_f32 v16, v0, v1
	v_cvt_pk_f16_f32 v17, v2, v3
	v_mul_f32_e32 v18, 0x41800000, v0
	v_mul_f32_e32 v19, 0x41800000, v1
	v_pk_mul_f32 v[118:119], v[128:129], v[118:119] op_sel_hi:[0,1]
	v_pk_mul_f32 v[124:125], v[128:129], v[124:125] op_sel_hi:[0,1]
	v_pk_mul_f32 v[126:127], v[128:129], v[126:127] op_sel_hi:[0,1]
	v_pk_fma_f32 v[4:5], v[12:13], v[116:117], v[4:5]
	global_store_dwordx2 v[32:33], v[16:17], off offset:2048
	v_med3_f32 v16, v18, s10, v39
	v_med3_f32 v17, v19, s10, v39
	v_pk_fma_f32 v[6:7], v[14:15], v[118:119], v[6:7]
	s_waitcnt lgkmcnt(0)
	v_pk_fma_f32 v[12:13], v[46:47], v[126:127], v[22:23]
	v_pk_fma_f32 v[14:15], v[44:45], v[124:125], v[20:21]
	v_mul_f32_e32 v20, 0x41800000, v2
	v_mul_f32_e32 v21, 0x41800000, v3
	v_mul_f32_e32 v22, 0x41800000, v4
	v_mul_f32_e32 v23, 0x41800000, v5
	v_cvt_pk_fp8_f32 v50, v16, v17
	v_med3_f32 v18, v20, s10, v39
	v_med3_f32 v19, v21, s10, v39
	v_med3_f32 v20, v22, s10, v39
	v_med3_f32 v21, v23, s10, v39
	v_cvt_pk_f16_f32 v0, v4, v5
	v_cvt_pk_f16_f32 v2, v10, v11
	v_mul_f32_e32 v10, 0x41800000, v10
	v_mul_f32_e32 v11, 0x41800000, v11
	v_cvt_pk_f16_f32 v4, v14, v15
	v_mul_f32_e32 v14, 0x41800000, v14
	v_mul_f32_e32 v15, 0x41800000, v15
	v_cvt_pk_fp8_f32 v52, v20, v21
	v_med3_f32 v10, v10, s10, v39
	v_med3_f32 v11, v11, s10, v39
	v_med3_f32 v14, v14, s10, v39
	v_med3_f32 v15, v15, s10, v39
	v_cvt_pk_f16_f32 v1, v6, v7
	v_mul_f32_e32 v6, 0x41800000, v6
	v_mul_f32_e32 v7, 0x41800000, v7
	v_cvt_pk_fp8_f32 v54, v10, v11
	v_cvt_pk_fp8_f32 v55, v14, v15
	v_cvt_pk_fp8_f32 v50, v18, v19 op_sel:[0,0,1]
	v_med3_f32 v6, v6, s10, v39
	v_med3_f32 v7, v7, s10, v39
	v_cvt_pk_f16_f32 v3, v8, v9
	v_mul_f32_e32 v8, 0x41800000, v8
	v_mul_f32_e32 v9, 0x41800000, v9
	v_cvt_pk_f16_f32 v5, v12, v13
	v_mul_f32_e32 v12, 0x41800000, v12
	v_mul_f32_e32 v13, 0x41800000, v13
	v_cvt_pk_fp8_f32 v52, v6, v7 op_sel:[0,0,1]
	v_med3_f32 v8, v8, s10, v39
	v_med3_f32 v9, v9, s10, v39
	v_med3_f32 v12, v12, s10, v39
	v_med3_f32 v13, v13, s10, v39
	v_cvt_pk_fp8_f32 v54, v8, v9 op_sel:[0,0,1]
	v_cvt_pk_fp8_f32 v55, v12, v13 op_sel:[0,0,1]
	global_store_dword v[30:31], v50, off offset:3072
	global_store_dwordx2 v[32:33], v[0:1], off offset:2560
	global_store_dword v[30:31], v52, off offset:3328
	global_store_dwordx2 v[32:33], v[2:3], off offset:3072
	global_store_dword v[30:31], v54, off offset:3584
	global_store_dwordx2 v[32:33], v[4:5], off offset:3584
	global_store_dword v[30:31], v55, off offset:3840
	s_cbranch_scc0 .Lp1_nopf3
	global_load_dwordx4 v[112:115], v[168:169], off nt
	global_load_dwordx4 v[116:119], v[168:169], off offset:1024 nt
	global_load_dwordx4 v[120:123], v[168:169], off offset:2048 nt
	global_load_dwordx4 v[124:127], v[168:169], off offset:3072 nt
.Lp1_nopf3:
	s_cbranch_scc1 .LBB0_116
